# code placement: P5 step loop moved from a 4-mod-8 byte offset to 0-mod-8 (one s_nop 0 before the loop label, one after the back-branch so later code keeps its phase); on top of v_rsl
# baseline (speedup 1.0000x reference)
; #define LAS __attribute__((address_space(3)))
;     ...
;                 const LAS float* sv = buf + ((bi * SB + s) * NV) * 64;
;                 const LAS f32x4* L4 = (const LAS f32x4*)sv;
;                 f32x2 qloa = {0.f, 0.f}, qhia = qloa, qlob = qloa, qhib = qloa, plo = qloa, phi = qloa, yloa = qloa, yhia = qloa, ylob = qloa, yhib = qloa, saq2 = qloa, sap2 = qloa;
;                 const float vv = sv[4 * 64 + lane]; const f32x2 vv2 = {vv, vv};
;                 const float xk = sv[1 * 64 + lane], xb = sv[2 * 64 + lane], xr = sv[5 * 64 + lane];
;                 float qd0 = 0.f, qd1 = 0.f, qd2 = 0.f, qd3 = 0.f, pd0 = 0.f, pd1 = 0.f, pd2 = 0.f, pd3 = 0.f, yd0 = 0.f, yd1 = 0.f, yd2 = 0.f, yd3 = 0.f, zd0 = 0.f, zd1 = 0.f, zd2 = 0.f, zd3 = 0.f;
;                 const int l15 = lane & 15; float xkq0 = sv[64 + l15], xkq1 = sv[64 + 16 + l15], xkq2 = sv[64 + 32 + l15], xkq3 = sv[64 + 48 + l15], xrq0 = sv[320 + l15], xrq1 = sv[320 + 16 + l15], xrq2 = sv[320 + 32 + l15], xrq3 = sv[320 + 48 + l15];
;     ...
;                 DPPFMAC(qd0, xkq0, Q2[0].x, 0); DPPFMAC(pd0, xkq0, P2[0].x, 0);
;                 DPPFMAC(qd1, xkq0, Q2[0].y, 1); DPPFMAC(pd1, xkq0, P2[0].y, 1);
;                 DPPFMAC(qd2, xkq0, Q2[1].x, 2); DPPFMAC(pd2, xkq0, P2[1].x, 2);
;                 DPPFMAC(qd3, xkq0, Q2[1].y, 3); DPPFMAC(pd3, xkq0, P2[1].y, 3);
;                 DPPFMAC(qd0, xkq0, Q2[2].x, 4); DPPFMAC(pd0, xkq0, P2[2].x, 4);
;                 DPPFMAC(qd1, xkq0, Q2[2].y, 5); DPPFMAC(pd1, xkq0, P2[2].y, 5);
;                 DPPFMAC(qd2, xkq0, Q2[3].x, 6); DPPFMAC(pd2, xkq0, P2[3].x, 6);
;                 DPPFMAC(qd3, xkq0, Q2[3].y, 7); DPPFMAC(pd3, xkq0, P2[3].y, 7);
;                 DPPFMAC(qd0, xkq0, Q2[4].x, 8); DPPFMAC(pd0, xkq0, P2[4].x, 8);
;                 DPPFMAC(qd1, xkq0, Q2[4].y, 9); DPPFMAC(pd1, xkq0, P2[4].y, 9);
;                 DPPFMAC(qd2, xkq0, Q2[5].x, 10); DPPFMAC(pd2, xkq0, P2[5].x, 10);
;                 DPPFMAC(qd3, xkq0, Q2[5].y, 11); DPPFMAC(pd3, xkq0, P2[5].y, 11);
;                 DPPFMAC(qd0, xkq0, Q2[6].x, 12); DPPFMAC(pd0, xkq0, P2[6].x, 12);
;                 DPPFMAC(qd1, xkq0, Q2[6].y, 13); DPPFMAC(pd1, xkq0, P2[6].y, 13);
;                 DPPFMAC(qd2, xkq0, Q2[7].x, 14); DPPFMAC(pd2, xkq0, P2[7].x, 14);
;                 DPPFMAC(qd3, xkq0, Q2[7].y, 15); DPPFMAC(pd3, xkq0, P2[7].y, 15);
.Lp5_norenorm:
	v_and_b32_e32 v255, 0xc0, v245
	v_add_u32_e32 v255, v255, v158
	v_add_u32_e32 v247, v245, v158
	ds_read_b32 v224, v247 offset:0
	ds_read_b32 v225, v247 offset:256
	ds_read_b32 v226, v247 offset:512
	ds_read_b32 v227, v247 offset:768
	ds_read_b32 v228, v247 offset:1280
	ds_read_b32 v229, v247 offset:1536
	ds_read_b32 v230, v247 offset:1792
	ds_read_b32 v231, v247 offset:2048
	ds_read_b32 v232, v247 offset:2304
	ds_read_b32 v233, v247 offset:2816
	s_waitcnt lgkmcnt(0)
	v_mul_f32_e32 v225, v225, v246
	v_mul_f32_e32 v246, v246, v224
	v_rcp_f32_e32 v234, v246
	v_mul_f32_e32 v228, v228, v246
	ds_write_b32 v247, v225 offset:256
	v_mul_f32_e32 v226, v226, v234
	v_mul_f32_e32 v227, v227, v234
	ds_write_b32 v247, v228 offset:1280
	ds_write_b32 v247, v226 offset:512
	ds_write_b32 v247, v227 offset:768
	v_mul_f32_e32 v230, v230, v246
	v_mul_f32_e32 v246, v246, v229
	v_rcp_f32_e32 v235, v246
	v_mul_f32_e32 v233, v233, v246
	ds_write_b32 v247, v230 offset:1792
	v_mul_f32_e32 v231, v231, v235
	v_mul_f32_e32 v232, v232, v235
	ds_write_b32 v247, v233 offset:2816
	ds_write_b32 v247, v231 offset:2048
	ds_write_b32 v247, v232 offset:2304
	s_waitcnt lgkmcnt(3)
	ds_read_b32 v224, v247 offset:3072
	ds_read_b32 v225, v247 offset:3328
	ds_read_b32 v226, v247 offset:3584
	ds_read_b32 v227, v247 offset:3840
	ds_read_b32 v228, v247 offset:4352
	ds_read_b32 v229, v247 offset:4608
	ds_read_b32 v230, v247 offset:4864
	ds_read_b32 v231, v247 offset:5120
	ds_read_b32 v232, v247 offset:5376
	ds_read_b32 v233, v247 offset:5888
	s_waitcnt lgkmcnt(0)
	v_mul_f32_e32 v225, v225, v246
	v_mul_f32_e32 v246, v246, v224
	v_rcp_f32_e32 v234, v246
	v_mul_f32_e32 v228, v228, v246
	ds_write_b32 v247, v225 offset:3328
	v_mul_f32_e32 v226, v226, v234
	v_mul_f32_e32 v227, v227, v234
	ds_write_b32 v247, v228 offset:4352
	ds_write_b32 v247, v226 offset:3584
	ds_write_b32 v247, v227 offset:3840
	v_mul_f32_e32 v230, v230, v246
	v_mul_f32_e32 v246, v246, v229
	v_rcp_f32_e32 v235, v246
	v_mul_f32_e32 v233, v233, v246
	ds_write_b32 v247, v230 offset:4864
	v_mul_f32_e32 v231, v231, v235
	v_mul_f32_e32 v232, v232, v235
	ds_write_b32 v247, v233 offset:5888
	ds_write_b32 v247, v231 offset:5120
	ds_write_b32 v247, v232 offset:5376
	ds_read_b128 v[192:195], v255 offset:256
	ds_read_b128 v[196:199], v255 offset:272
	ds_read_b128 v[200:203], v255 offset:288
	ds_read_b128 v[204:207], v255 offset:304
	s_waitcnt lgkmcnt(4)
	ds_read_b128 v[224:227], v255 offset:512
	ds_read_b128 v[228:231], v255 offset:528
	ds_read_b128 v[232:235], v255 offset:544
	ds_read_b128 v[236:239], v255 offset:560
	ds_read_b128 v[240:243], v255 offset:768
	ds_read_b128 v[166:169], v255 offset:784
	ds_read_b128 v[170:173], v255 offset:800
	ds_read_b128 v[174:177], v255 offset:816
	ds_read_b32 v254, v247 offset:1024
	s_nop 0
.Lp5_step:
	s_waitcnt lgkmcnt(0)
	v_mul_f32_e32 v208, v0, v192
	v_mul_f32_e32 v212, v64, v192
	v_mul_f32_e32 v209, v1, v192
	v_mul_f32_e32 v213, v65, v192
	v_mul_f32_e32 v210, v2, v192
	v_mul_f32_e32 v214, v66, v192
	v_mul_f32_e32 v211, v3, v192
	v_mul_f32_e32 v215, v67, v192
	v_fmac_f32_e32 v208, v4, v193
	v_fmac_f32_e32 v212, v68, v193
	v_fmac_f32_e32 v209, v5, v193
	v_fmac_f32_e32 v213, v69, v193
	v_fmac_f32_e32 v210, v6, v193
	v_fmac_f32_e32 v214, v70, v193
	v_fmac_f32_e32 v211, v7, v193
	v_fmac_f32_e32 v215, v71, v193
	v_fmac_f32_e32 v208, v8, v194
	v_fmac_f32_e32 v212, v72, v194
	v_fmac_f32_e32 v209, v9, v194
	v_fmac_f32_e32 v213, v73, v194
	v_fmac_f32_e32 v210, v10, v194
	v_fmac_f32_e32 v214, v74, v194
	v_fmac_f32_e32 v211, v11, v194
	v_fmac_f32_e32 v215, v75, v194
	v_fmac_f32_e32 v208, v12, v195
	v_fmac_f32_e32 v212, v76, v195
	v_fmac_f32_e32 v209, v13, v195
	v_fmac_f32_e32 v213, v77, v195
	v_fmac_f32_e32 v210, v14, v195
	v_fmac_f32_e32 v214, v78, v195
	v_fmac_f32_e32 v211, v15, v195
	v_fmac_f32_e32 v215, v79, v195
	v_fmac_f32_e32 v208, v16, v196
	v_fmac_f32_e32 v212, v80, v196
	v_fmac_f32_e32 v209, v17, v196
	v_fmac_f32_e32 v213, v81, v196
	v_fmac_f32_e32 v210, v18, v196
	v_fmac_f32_e32 v214, v82, v196
	v_fmac_f32_e32 v211, v19, v196
	v_fmac_f32_e32 v215, v83, v196
	v_fmac_f32_e32 v208, v20, v197
	v_fmac_f32_e32 v212, v84, v197
	v_fmac_f32_e32 v209, v21, v197
	v_fmac_f32_e32 v213, v85, v197
	v_fmac_f32_e32 v210, v22, v197
	v_fmac_f32_e32 v214, v86, v197
	v_fmac_f32_e32 v211, v23, v197
	v_fmac_f32_e32 v215, v87, v197
	v_fmac_f32_e32 v208, v24, v198
	v_fmac_f32_e32 v212, v88, v198
	v_fmac_f32_e32 v209, v25, v198
	v_fmac_f32_e32 v213, v89, v198
	v_fmac_f32_e32 v210, v26, v198
	v_fmac_f32_e32 v214, v90, v198
	v_fmac_f32_e32 v211, v27, v198
	v_fmac_f32_e32 v215, v91, v198
	v_fmac_f32_e32 v208, v28, v199
	v_fmac_f32_e32 v212, v92, v199
	v_fmac_f32_e32 v209, v29, v199
	v_fmac_f32_e32 v213, v93, v199
	v_fmac_f32_e32 v210, v30, v199
	v_fmac_f32_e32 v214, v94, v199
	v_fmac_f32_e32 v211, v31, v199
	v_fmac_f32_e32 v215, v95, v199
	v_fmac_f32_e32 v208, v32, v200
	v_fmac_f32_e32 v212, v96, v200
	v_fmac_f32_e32 v209, v33, v200
	v_fmac_f32_e32 v213, v97, v200
	v_fmac_f32_e32 v210, v34, v200
	v_fmac_f32_e32 v214, v98, v200
	v_fmac_f32_e32 v211, v35, v200
	v_fmac_f32_e32 v215, v99, v200
	v_fmac_f32_e32 v208, v36, v201
	v_fmac_f32_e32 v212, v100, v201
	v_fmac_f32_e32 v209, v37, v201
	v_fmac_f32_e32 v213, v101, v201
	v_fmac_f32_e32 v210, v38, v201
	v_fmac_f32_e32 v214, v102, v201
	v_fmac_f32_e32 v211, v39, v201
	v_fmac_f32_e32 v215, v103, v201
	v_fmac_f32_e32 v208, v40, v202
	v_fmac_f32_e32 v212, v104, v202
	v_fmac_f32_e32 v209, v41, v202
	v_fmac_f32_e32 v213, v105, v202
	v_fmac_f32_e32 v210, v42, v202
	v_fmac_f32_e32 v214, v106, v202
	v_fmac_f32_e32 v211, v43, v202
	v_fmac_f32_e32 v215, v107, v202
;     ...
;                 { const float saq = -((qd0 + qd1) + (qd2 + qd3)), sap = -((pd0 + pd1) + (pd2 + pd3)); saq2 = (f32x2){saq, saq}; sap2 = (f32x2){sap, sap}; }
;                 __builtin_amdgcn_sched_barrier(0);
;                 f32x4 d_2 = L4[2], b_2 = L4[34], k_2 = L4[50];
;                 f32x4 d_3 = L4[3], b_3 = L4[35], k_3 = L4[51];
;                 asm volatile("s_nop 1" : "+v"(xrq0), "+v"(xrq1), "+v"(xrq2), "+v"(xrq3));
;                 { const f32x2 bxy = b_0.xy, bzw = b_0.zw;
;                 Q2[0] = Q2[0] * d_0.xy + (saq2 * bxy + vv2 * k_0.xy); Q2[1] = Q2[1] * d_0.zw + (saq2 * bzw + vv2 * k_0.zw);
;                 P2[0] = P2[0] * d_0.xy + sap2 * bxy; P2[1] = P2[1] * d_0.zw + sap2 * bzw;
;                 DPPFMAC(yd0, xrq0, Q2[0].x, 0); DPPFMAC(zd0, xrq0, P2[0].x, 0);
;                 DPPFMAC(yd1, xrq0, Q2[0].y, 1); DPPFMAC(zd1, xrq0, P2[0].y, 1);
;                 DPPFMAC(yd2, xrq0, Q2[1].x, 2); DPPFMAC(zd2, xrq0, P2[1].x, 2);
;                 DPPFMAC(yd3, xrq0, Q2[1].y, 3); DPPFMAC(zd3, xrq0, P2[1].y, 3);
;                 }
;                 { const f32x2 bxy = b_1.xy, bzw = b_1.zw;
;                 Q2[2] = Q2[2] * d_1.xy + (saq2 * bxy + vv2 * k_1.xy); Q2[3] = Q2[3] * d_1.zw + (saq2 * bzw + vv2 * k_1.zw);
;                 P2[2] = P2[2] * d_1.xy + sap2 * bxy; P2[3] = P2[3] * d_1.zw + sap2 * bzw;
;                 DPPFMAC(yd0, xrq0, Q2[2].x, 4); DPPFMAC(zd0, xrq0, P2[2].x, 4);
;                 DPPFMAC(yd1, xrq0, Q2[2].y, 5); DPPFMAC(zd1, xrq0, P2[2].y, 5);
;                 DPPFMAC(yd2, xrq0, Q2[3].x, 6); DPPFMAC(zd2, xrq0, P2[3].x, 6);
;                 DPPFMAC(yd3, xrq0, Q2[3].y, 7); DPPFMAC(zd3, xrq0, P2[3].y, 7);
;                 }
;                 __builtin_amdgcn_sched_barrier(0);
;                 f32x4 d_4 = L4[4], b_4 = L4[36], k_4 = L4[52];
;                 f32x4 d_5 = L4[5], b_5 = L4[37], k_5 = L4[53];
;                 { const f32x2 bxy = b_2.xy, bzw = b_2.zw;
;                 Q2[4] = Q2[4] * d_2.xy + (saq2 * bxy + vv2 * k_2.xy); Q2[5] = Q2[5] * d_2.zw + (saq2 * bzw + vv2 * k_2.zw);
;                 P2[4] = P2[4] * d_2.xy + sap2 * bxy; P2[5] = P2[5] * d_2.zw + sap2 * bzw;
;                 DPPFMAC(yd0, xrq0, Q2[4].x, 8); DPPFMAC(zd0, xrq0, P2[4].x, 8);
;                 DPPFMAC(yd1, xrq0, Q2[4].y, 9); DPPFMAC(zd1, xrq0, P2[4].y, 9);
;                 DPPFMAC(yd2, xrq0, Q2[5].x, 10); DPPFMAC(zd2, xrq0, P2[5].x, 10);
	v_fmac_f32_e32 v208, v44, v203
	v_fmac_f32_e32 v212, v108, v203
	v_fmac_f32_e32 v209, v45, v203
	v_fmac_f32_e32 v213, v109, v203
	v_fmac_f32_e32 v210, v46, v203
	v_fmac_f32_e32 v214, v110, v203
	v_fmac_f32_e32 v211, v47, v203
	v_fmac_f32_e32 v215, v111, v203
	v_fmac_f32_e32 v208, v48, v204
	v_fmac_f32_e32 v212, v112, v204
	v_fmac_f32_e32 v209, v49, v204
	v_fmac_f32_e32 v213, v113, v204
	v_fmac_f32_e32 v210, v50, v204
	v_fmac_f32_e32 v214, v114, v204
	v_fmac_f32_e32 v211, v51, v204
	v_fmac_f32_e32 v215, v115, v204
	v_fmac_f32_e32 v208, v52, v205
	v_fmac_f32_e32 v212, v116, v205
	v_fmac_f32_e32 v209, v53, v205
	v_fmac_f32_e32 v213, v117, v205
	v_fmac_f32_e32 v210, v54, v205
	v_fmac_f32_e32 v214, v118, v205
	v_fmac_f32_e32 v211, v55, v205
	v_fmac_f32_e32 v215, v119, v205
	v_fmac_f32_e32 v208, v56, v206
	v_fmac_f32_e32 v212, v120, v206
	v_fmac_f32_e32 v209, v57, v206
	v_fmac_f32_e32 v213, v121, v206
	v_fmac_f32_e32 v210, v58, v206
	v_fmac_f32_e32 v214, v122, v206
	v_fmac_f32_e32 v211, v59, v206
	v_fmac_f32_e32 v215, v123, v206
	v_fmac_f32_e32 v208, v60, v207
	v_fmac_f32_e32 v212, v124, v207
	v_fmac_f32_e32 v209, v61, v207
	v_fmac_f32_e32 v213, v125, v207
	v_fmac_f32_e32 v210, v62, v207
	v_fmac_f32_e32 v214, v126, v207
	v_fmac_f32_e32 v211, v63, v207
	v_fmac_f32_e32 v215, v127, v207
	ds_read_b128 v[192:195], v255 offset:1280
	ds_read_b128 v[196:199], v255 offset:1296
	ds_read_b128 v[200:203], v255 offset:1312
	ds_read_b128 v[204:207], v255 offset:1328
	v_add_f32_dpp v208, v208, v208 quad_perm:[1,0,3,2] row_mask:0xf bank_mask:0xf
	v_add_f32_dpp v209, v209, v209 quad_perm:[1,0,3,2] row_mask:0xf bank_mask:0xf
	v_add_f32_dpp v210, v210, v210 quad_perm:[1,0,3,2] row_mask:0xf bank_mask:0xf
	v_add_f32_dpp v211, v211, v211 quad_perm:[1,0,3,2] row_mask:0xf bank_mask:0xf
	v_add_f32_dpp v212, v212, v212 quad_perm:[1,0,3,2] row_mask:0xf bank_mask:0xf
	v_add_f32_dpp v213, v213, v213 quad_perm:[1,0,3,2] row_mask:0xf bank_mask:0xf
	v_add_f32_dpp v214, v214, v214 quad_perm:[1,0,3,2] row_mask:0xf bank_mask:0xf
	v_add_f32_dpp v215, v215, v215 quad_perm:[1,0,3,2] row_mask:0xf bank_mask:0xf
	v_add_f32_dpp v208, v208, v208 quad_perm:[2,3,0,1] row_mask:0xf bank_mask:0xf
	v_add_f32_dpp v209, v209, v209 quad_perm:[2,3,0,1] row_mask:0xf bank_mask:0xf
	v_add_f32_dpp v210, v210, v210 quad_perm:[2,3,0,1] row_mask:0xf bank_mask:0xf
	v_add_f32_dpp v211, v211, v211 quad_perm:[2,3,0,1] row_mask:0xf bank_mask:0xf
	v_add_f32_dpp v212, v212, v212 quad_perm:[2,3,0,1] row_mask:0xf bank_mask:0xf
	v_add_f32_dpp v213, v213, v213 quad_perm:[2,3,0,1] row_mask:0xf bank_mask:0xf
	v_add_f32_dpp v214, v214, v214 quad_perm:[2,3,0,1] row_mask:0xf bank_mask:0xf
	v_add_f32_dpp v215, v215, v215 quad_perm:[2,3,0,1] row_mask:0xf bank_mask:0xf
	v_cndmask_b32_e64 v178, -v208, -v209, s[86:87]
	v_cndmask_b32_e64 v179, -v212, -v213, s[86:87]
	v_cndmask_b32_e64 v178, v178, -v210, s[88:89]
	v_cndmask_b32_e64 v179, v179, -v214, s[88:89]
	v_cndmask_b32_e64 v178, v178, -v211, s[84:85]
	v_cndmask_b32_e64 v179, v179, -v215, s[84:85]
	s_nop 1
	v_mfma_f32_4x4x1_16b_f32 v[0:3], v178, v224, v[0:3]
	v_mfma_f32_4x4x1_16b_f32 v[64:67], v179, v224, v[64:67]
	v_mfma_f32_4x4x1_16b_f32 v[4:7], v178, v225, v[4:7]
	v_mfma_f32_4x4x1_16b_f32 v[68:71], v179, v225, v[68:71]
	v_mfma_f32_4x4x1_16b_f32 v[0:3], v254, v240, v[0:3]
	v_mfma_f32_4x4x1_16b_f32 v[8:11], v178, v226, v[8:11]
	v_mfma_f32_4x4x1_16b_f32 v[72:75], v179, v226, v[72:75]
	v_mfma_f32_4x4x1_16b_f32 v[4:7], v254, v241, v[4:7]
	s_waitcnt lgkmcnt(0)
	v_mfma_f32_4x4x1_16b_f32 v[12:15], v178, v227, v[12:15]
	v_mul_f32_e32 v208, v0, v192
	v_mul_f32_e32 v212, v64, v192
	v_mul_f32_e32 v209, v1, v192
	v_mul_f32_e32 v213, v65, v192
	v_mfma_f32_4x4x1_16b_f32 v[76:79], v179, v227, v[76:79]
	v_mul_f32_e32 v210, v2, v192
	v_mul_f32_e32 v214, v66, v192
	v_mul_f32_e32 v211, v3, v192
	v_mul_f32_e32 v215, v67, v192
	v_mfma_f32_4x4x1_16b_f32 v[8:11], v254, v242, v[8:11]
	v_mfma_f32_4x4x1_16b_f32 v[16:19], v178, v228, v[16:19]
	v_fmac_f32_e32 v208, v4, v193
	v_fmac_f32_e32 v212, v68, v193
	v_fmac_f32_e32 v209, v5, v193
	v_fmac_f32_e32 v213, v69, v193
	v_mfma_f32_4x4x1_16b_f32 v[80:83], v179, v228, v[80:83]
	v_fmac_f32_e32 v210, v6, v193
	v_fmac_f32_e32 v214, v70, v193
	v_fmac_f32_e32 v211, v7, v193
	v_fmac_f32_e32 v215, v71, v193
	v_mfma_f32_4x4x1_16b_f32 v[12:15], v254, v243, v[12:15]
	v_mfma_f32_4x4x1_16b_f32 v[20:23], v178, v229, v[20:23]
	v_fmac_f32_e32 v208, v8, v194
	v_fmac_f32_e32 v212, v72, v194
	v_fmac_f32_e32 v209, v9, v194
	v_fmac_f32_e32 v213, v73, v194
	v_mfma_f32_4x4x1_16b_f32 v[84:87], v179, v229, v[84:87]
	v_fmac_f32_e32 v210, v10, v194
	v_fmac_f32_e32 v214, v74, v194
	v_fmac_f32_e32 v211, v11, v194
	v_fmac_f32_e32 v215, v75, v194
	v_mfma_f32_4x4x1_16b_f32 v[16:19], v254, v166, v[16:19]
	v_mfma_f32_4x4x1_16b_f32 v[24:27], v178, v230, v[24:27]
	v_fmac_f32_e32 v208, v12, v195
	v_fmac_f32_e32 v212, v76, v195
	v_fmac_f32_e32 v209, v13, v195
	v_fmac_f32_e32 v213, v77, v195
	v_mfma_f32_4x4x1_16b_f32 v[88:91], v179, v230, v[88:91]
	v_fmac_f32_e32 v210, v14, v195
	v_fmac_f32_e32 v214, v78, v195
	v_fmac_f32_e32 v211, v15, v195
	v_fmac_f32_e32 v215, v79, v195
	v_mfma_f32_4x4x1_16b_f32 v[20:23], v254, v167, v[20:23]
	v_mfma_f32_4x4x1_16b_f32 v[28:31], v178, v231, v[28:31]
	v_fmac_f32_e32 v208, v16, v196
	v_fmac_f32_e32 v212, v80, v196
	v_fmac_f32_e32 v209, v17, v196
	v_fmac_f32_e32 v213, v81, v196
	v_mfma_f32_4x4x1_16b_f32 v[92:95], v179, v231, v[92:95]
	v_fmac_f32_e32 v210, v18, v196
	v_fmac_f32_e32 v214, v82, v196
	v_fmac_f32_e32 v211, v19, v196
	v_fmac_f32_e32 v215, v83, v196
	v_mfma_f32_4x4x1_16b_f32 v[24:27], v254, v168, v[24:27]
	v_mfma_f32_4x4x1_16b_f32 v[32:35], v178, v232, v[32:35]
;     ...
;                 __builtin_amdgcn_sched_barrier(0);
;                 f32x4 d_12 = L4[12], b_12 = L4[44], k_12 = L4[60];
;                 f32x4 d_13 = L4[13], b_13 = L4[45], k_13 = L4[61];
;                 { const f32x2 bxy = b_10.xy, bzw = b_10.zw;
;                 Q2[20] = Q2[20] * d_10.xy + (saq2 * bxy + vv2 * k_10.xy); Q2[21] = Q2[21] * d_10.zw + (saq2 * bzw + vv2 * k_10.zw);
;                 P2[20] = P2[20] * d_10.xy + sap2 * bxy; P2[21] = P2[21] * d_10.zw + sap2 * bzw;
;                 DPPFMAC(yd0, xrq2, Q2[20].x, 8); DPPFMAC(zd0, xrq2, P2[20].x, 8);
;                 DPPFMAC(yd1, xrq2, Q2[20].y, 9); DPPFMAC(zd1, xrq2, P2[20].y, 9);
;                 DPPFMAC(yd2, xrq2, Q2[21].x, 10); DPPFMAC(zd2, xrq2, P2[21].x, 10);
;                 DPPFMAC(yd3, xrq2, Q2[21].y, 11); DPPFMAC(zd3, xrq2, P2[21].y, 11);
;                 }
;                 { const f32x2 bxy = b_11.xy, bzw = b_11.zw;
;                 Q2[22] = Q2[22] * d_11.xy + (saq2 * bxy + vv2 * k_11.xy); Q2[23] = Q2[23] * d_11.zw + (saq2 * bzw + vv2 * k_11.zw);
;                 P2[22] = P2[22] * d_11.xy + sap2 * bxy; P2[23] = P2[23] * d_11.zw + sap2 * bzw;
;                 DPPFMAC(yd0, xrq2, Q2[22].x, 12); DPPFMAC(zd0, xrq2, P2[22].x, 12);
;                 DPPFMAC(yd1, xrq2, Q2[22].y, 13); DPPFMAC(zd1, xrq2, P2[22].y, 13);
;                 DPPFMAC(yd2, xrq2, Q2[23].x, 14); DPPFMAC(zd2, xrq2, P2[23].x, 14);
;                 DPPFMAC(yd3, xrq2, Q2[23].y, 15); DPPFMAC(zd3, xrq2, P2[23].y, 15);
;                 }
;                 __builtin_amdgcn_sched_barrier(0);
;                 f32x4 d_14 = L4[14], b_14 = L4[46], k_14 = L4[62];
;                 f32x4 d_15 = L4[15], b_15 = L4[47], k_15 = L4[63];
;                 { const f32x2 bxy = b_12.xy, bzw = b_12.zw;
;                 Q2[24] = Q2[24] * d_12.xy + (saq2 * bxy + vv2 * k_12.xy); Q2[25] = Q2[25] * d_12.zw + (saq2 * bzw + vv2 * k_12.zw);
;                 P2[24] = P2[24] * d_12.xy + sap2 * bxy; P2[25] = P2[25] * d_12.zw + sap2 * bzw;
;                 DPPFMAC(yd0, xrq3, Q2[24].x, 0); DPPFMAC(zd0, xrq3, P2[24].x, 0);
;                 DPPFMAC(yd1, xrq3, Q2[24].y, 1); DPPFMAC(zd1, xrq3, P2[24].y, 1);
;                 DPPFMAC(yd2, xrq3, Q2[25].x, 2); DPPFMAC(zd2, xrq3, P2[25].x, 2);
;                 DPPFMAC(yd3, xrq3, Q2[25].y, 3); DPPFMAC(zd3, xrq3, P2[25].y, 3);
;                 }
	v_fmac_f32_e32 v208, v20, v197
	v_fmac_f32_e32 v212, v84, v197
	v_fmac_f32_e32 v209, v21, v197
	v_fmac_f32_e32 v213, v85, v197
	v_mfma_f32_4x4x1_16b_f32 v[96:99], v179, v232, v[96:99]
	v_fmac_f32_e32 v210, v22, v197
	v_fmac_f32_e32 v214, v86, v197
	v_fmac_f32_e32 v211, v23, v197
	v_fmac_f32_e32 v215, v87, v197
	v_mfma_f32_4x4x1_16b_f32 v[28:31], v254, v169, v[28:31]
	v_mfma_f32_4x4x1_16b_f32 v[36:39], v178, v233, v[36:39]
	v_fmac_f32_e32 v208, v24, v198
	v_fmac_f32_e32 v212, v88, v198
	v_fmac_f32_e32 v209, v25, v198
	v_fmac_f32_e32 v213, v89, v198
	v_mfma_f32_4x4x1_16b_f32 v[100:103], v179, v233, v[100:103]
	v_fmac_f32_e32 v210, v26, v198
	v_fmac_f32_e32 v214, v90, v198
	v_fmac_f32_e32 v211, v27, v198
	v_fmac_f32_e32 v215, v91, v198
	v_mfma_f32_4x4x1_16b_f32 v[32:35], v254, v170, v[32:35]
	v_mfma_f32_4x4x1_16b_f32 v[40:43], v178, v234, v[40:43]
	v_fmac_f32_e32 v208, v28, v199
	v_fmac_f32_e32 v212, v92, v199
	v_fmac_f32_e32 v209, v29, v199
	v_fmac_f32_e32 v213, v93, v199
	v_mfma_f32_4x4x1_16b_f32 v[104:107], v179, v234, v[104:107]
	v_fmac_f32_e32 v210, v30, v199
	v_fmac_f32_e32 v214, v94, v199
	v_fmac_f32_e32 v211, v31, v199
	v_fmac_f32_e32 v215, v95, v199
	v_mfma_f32_4x4x1_16b_f32 v[36:39], v254, v171, v[36:39]
	v_mfma_f32_4x4x1_16b_f32 v[44:47], v178, v235, v[44:47]
	v_fmac_f32_e32 v208, v32, v200
	v_fmac_f32_e32 v212, v96, v200
	v_fmac_f32_e32 v209, v33, v200
	v_fmac_f32_e32 v213, v97, v200
	v_mfma_f32_4x4x1_16b_f32 v[108:111], v179, v235, v[108:111]
	v_fmac_f32_e32 v210, v34, v200
	v_fmac_f32_e32 v214, v98, v200
	v_fmac_f32_e32 v211, v35, v200
	v_fmac_f32_e32 v215, v99, v200
	v_mfma_f32_4x4x1_16b_f32 v[40:43], v254, v172, v[40:43]
	v_mfma_f32_4x4x1_16b_f32 v[48:51], v178, v236, v[48:51]
	v_fmac_f32_e32 v208, v36, v201
	v_fmac_f32_e32 v212, v100, v201
	v_fmac_f32_e32 v209, v37, v201
	v_fmac_f32_e32 v213, v101, v201
	v_mfma_f32_4x4x1_16b_f32 v[112:115], v179, v236, v[112:115]
	v_fmac_f32_e32 v210, v38, v201
	v_fmac_f32_e32 v214, v102, v201
	v_fmac_f32_e32 v211, v39, v201
	v_fmac_f32_e32 v215, v103, v201
	v_mfma_f32_4x4x1_16b_f32 v[44:47], v254, v173, v[44:47]
	v_mfma_f32_4x4x1_16b_f32 v[52:55], v178, v237, v[52:55]
	v_fmac_f32_e32 v208, v40, v202
	v_fmac_f32_e32 v212, v104, v202
	v_fmac_f32_e32 v209, v41, v202
	v_fmac_f32_e32 v213, v105, v202
	v_mfma_f32_4x4x1_16b_f32 v[116:119], v179, v237, v[116:119]
	v_fmac_f32_e32 v210, v42, v202
	v_fmac_f32_e32 v214, v106, v202
	v_fmac_f32_e32 v211, v43, v202
	v_fmac_f32_e32 v215, v107, v202
	v_mfma_f32_4x4x1_16b_f32 v[48:51], v254, v174, v[48:51]
	v_mfma_f32_4x4x1_16b_f32 v[56:59], v178, v238, v[56:59]
	v_fmac_f32_e32 v208, v44, v203
	v_fmac_f32_e32 v212, v108, v203
	v_fmac_f32_e32 v209, v45, v203
	v_fmac_f32_e32 v213, v109, v203
	v_mfma_f32_4x4x1_16b_f32 v[120:123], v179, v238, v[120:123]
	v_fmac_f32_e32 v210, v46, v203
	v_fmac_f32_e32 v214, v110, v203
	v_fmac_f32_e32 v211, v47, v203
	v_fmac_f32_e32 v215, v111, v203
	v_mfma_f32_4x4x1_16b_f32 v[52:55], v254, v175, v[52:55]
	v_mfma_f32_4x4x1_16b_f32 v[60:63], v178, v239, v[60:63]
	v_fmac_f32_e32 v208, v48, v204
	v_fmac_f32_e32 v212, v112, v204
	v_fmac_f32_e32 v209, v49, v204
	v_fmac_f32_e32 v213, v113, v204
	v_mfma_f32_4x4x1_16b_f32 v[124:127], v179, v239, v[124:127]
	v_fmac_f32_e32 v210, v50, v204
	v_fmac_f32_e32 v214, v114, v204
	v_fmac_f32_e32 v211, v51, v204
	v_fmac_f32_e32 v215, v115, v204
	v_mfma_f32_4x4x1_16b_f32 v[56:59], v254, v176, v[56:59]
	v_fmac_f32_e32 v208, v52, v205
	v_fmac_f32_e32 v212, v116, v205
	v_fmac_f32_e32 v209, v53, v205
	v_fmac_f32_e32 v213, v117, v205
	v_fmac_f32_e32 v210, v54, v205
	v_fmac_f32_e32 v214, v118, v205
	v_fmac_f32_e32 v211, v55, v205
	v_fmac_f32_e32 v215, v119, v205
	v_mfma_f32_4x4x1_16b_f32 v[60:63], v254, v177, v[60:63]
	ds_read_b128 v[224:227], v255 offset:2048
	ds_read_b128 v[228:231], v255 offset:2064
	ds_read_b128 v[232:235], v255 offset:2080
	ds_read_b128 v[236:239], v255 offset:2096
	ds_read_b128 v[240:243], v255 offset:2304
	ds_read_b128 v[166:169], v255 offset:2320
	ds_read_b128 v[170:173], v255 offset:2336
	ds_read_b128 v[174:177], v255 offset:2352
	ds_read_b32 v254, v247 offset:2560
	v_fmac_f32_e32 v208, v56, v206
	v_fmac_f32_e32 v212, v120, v206
	v_fmac_f32_e32 v209, v57, v206
	v_fmac_f32_e32 v213, v121, v206
	v_fmac_f32_e32 v210, v58, v206
	v_fmac_f32_e32 v214, v122, v206
	v_fmac_f32_e32 v211, v59, v206
	v_fmac_f32_e32 v215, v123, v206
	v_fmac_f32_e32 v208, v60, v207
	v_fmac_f32_e32 v212, v124, v207
	v_fmac_f32_e32 v209, v61, v207
	v_fmac_f32_e32 v213, v125, v207
	v_fmac_f32_e32 v210, v62, v207
	v_fmac_f32_e32 v214, v126, v207
	v_fmac_f32_e32 v211, v63, v207
	v_fmac_f32_e32 v215, v127, v207
	ds_read_b128 v[192:195], v255 offset:1792
	ds_read_b128 v[196:199], v255 offset:1808
	ds_read_b128 v[200:203], v255 offset:1824
	ds_read_b128 v[204:207], v255 offset:1840
	v_add_f32_dpp v208, v208, v208 quad_perm:[1,0,3,2] row_mask:0xf bank_mask:0xf
	v_add_f32_dpp v209, v209, v209 quad_perm:[1,0,3,2] row_mask:0xf bank_mask:0xf
	v_add_f32_dpp v210, v210, v210 quad_perm:[1,0,3,2] row_mask:0xf bank_mask:0xf
	v_add_f32_dpp v211, v211, v211 quad_perm:[1,0,3,2] row_mask:0xf bank_mask:0xf
	v_add_f32_dpp v212, v212, v212 quad_perm:[1,0,3,2] row_mask:0xf bank_mask:0xf
	v_add_f32_dpp v213, v213, v213 quad_perm:[1,0,3,2] row_mask:0xf bank_mask:0xf
	v_add_f32_dpp v214, v214, v214 quad_perm:[1,0,3,2] row_mask:0xf bank_mask:0xf
	v_add_f32_dpp v215, v215, v215 quad_perm:[1,0,3,2] row_mask:0xf bank_mask:0xf
	v_add_f32_dpp v208, v208, v208 quad_perm:[2,3,0,1] row_mask:0xf bank_mask:0xf
	v_add_f32_dpp v209, v209, v209 quad_perm:[2,3,0,1] row_mask:0xf bank_mask:0xf
	v_add_f32_dpp v210, v210, v210 quad_perm:[2,3,0,1] row_mask:0xf bank_mask:0xf
	v_add_f32_dpp v211, v211, v211 quad_perm:[2,3,0,1] row_mask:0xf bank_mask:0xf
	v_add_f32_dpp v212, v212, v212 quad_perm:[2,3,0,1] row_mask:0xf bank_mask:0xf
	v_add_f32_dpp v213, v213, v213 quad_perm:[2,3,0,1] row_mask:0xf bank_mask:0xf
	v_add_f32_dpp v214, v214, v214 quad_perm:[2,3,0,1] row_mask:0xf bank_mask:0xf
	v_add_f32_dpp v215, v215, v215 quad_perm:[2,3,0,1] row_mask:0xf bank_mask:0xf
	v_cndmask_b32_e64 v178, v208, v209, s[86:87]
	v_cndmask_b32_e64 v179, v212, v213, s[86:87]
	v_cndmask_b32_e64 v178, v178, v210, s[88:89]
	v_cndmask_b32_e64 v179, v179, v214, s[88:89]
	v_cndmask_b32_e64 v178, v178, v211, s[84:85]
	v_cndmask_b32_e64 v179, v179, v215, s[84:85]
	v_add_u32_e32 v130, s45, v141
	v_lshl_add_u64 v[216:217], v[130:131], 2, s[26:27]
	v_lshl_add_u64 v[218:219], v[130:131], 1, s[12:13]
	v_bfe_u32 v130, v179, 16, 1
	v_add3_u32 v130, v179, v130, s41
	s_addk_i32 s45, 0x400
	v_add_u32_e32 v255, 0x600, v255
	v_add_u32_e32 v247, 0x600, v247
	global_store_dword v[216:217], v178, off
	global_store_short_d16_hi v[218:219], v130, off
	s_cmpk_eq_i32 s45, 0x1000
	s_cbranch_scc0 .Lp5_step
;     ...
;             asm volatile("" ::: "memory");
;             if (MODE != 2 && seg + 1 < CL / SB) SCAN_STORE(bi ^ 1, seg + 1);
;             asm volatile("" ::: "memory");
	s_nop 0
	s_waitcnt lgkmcnt(0)
	s_andn2_b64 vcc, exec, s[66:67]
	s_cbranch_vccnz .LBB0_1077
	s_waitcnt vmcnt(26)
	v_lshlrev_b32_e32 v142, 16, v133
	s_waitcnt vmcnt(25)
	v_lshlrev_b32_e32 v146, 16, v135
	s_waitcnt vmcnt(23)
	v_lshlrev_b32_e32 v148, 16, v137
	s_waitcnt vmcnt(22)
	v_lshlrev_b32_e32 v149, 16, v150
	s_waitcnt vmcnt(21)
	v_lshlrev_b32_e32 v133, 16, v154
	s_waitcnt vmcnt(20)
	v_lshlrev_b32_e32 v143, 16, v248
	s_waitcnt vmcnt(19)
	v_lshlrev_b32_e32 v135, 16, v249
	s_waitcnt vmcnt(18)
	v_lshlrev_b32_e32 v150, 16, v250
	s_waitcnt vmcnt(17)
	v_lshlrev_b32_e32 v152, 16, v251
	s_waitcnt vmcnt(16)
	v_lshlrev_b32_e32 v137, 16, v252
	s_waitcnt vmcnt(15)
	v_lshlrev_b32_e32 v154, 16, v253
	s_waitcnt vmcnt(13)
	v_lshlrev_b32_e32 v153, 16, v220
	s_waitcnt vmcnt(12)
	v_lshlrev_b32_e32 v160, 16, v221
	s_waitcnt vmcnt(11)
	v_lshlrev_b32_e32 v162, 16, v162
	s_waitcnt vmcnt(10)
	v_lshlrev_b32_e32 v161, 16, v163
	s_waitcnt vmcnt(9)
	v_lshlrev_b32_e32 v163, 16, v222
	v_sub_f32_e32 v157, v157, v142
	v_sub_f32_e32 v130, v159, v143
	v_fma_f32 v157, v183, v157, v142
	v_add_f32_e32 v159, -1.0, v146
	v_mul_f32_e32 v158, v185, v157
	v_fma_f32 v159, v186, v159, 1.0
	v_fma_f32 v130, v182, v130, v143
	v_mul_f32_e32 v157, v159, v157
	v_mul_f32_e32 v159, v158, v158
	v_mul_f32_e32 v165, v130, v157
	v_mul_f32_e32 v166, v187, v165
	v_mov_b32_dpp v159, v159 row_shr:1 row_mask:0xf bank_mask:0xf bound_ctrl:1
	v_fmac_f32_e32 v159, v158, v158
	v_mov_b32_dpp v166, v166 row_shr:1 row_mask:0xf bank_mask:0xf bound_ctrl:1
	v_fmac_f32_e32 v166, v187, v165
	v_add_f32_dpp v159, v159, v159 row_shr:2 row_mask:0xf bank_mask:0xf bound_ctrl:1
	s_lshl_b32 s43, s43, 2
	v_add_f32_dpp v165, v166, v166 row_shr:2 row_mask:0xf bank_mask:0xf bound_ctrl:1
	v_add_f32_dpp v159, v159, v159 row_shr:4 row_mask:0xf bank_mask:0xf bound_ctrl:1
	v_mov_b32_e32 v166, v131
	v_add_f32_dpp v165, v165, v165 row_shr:4 row_mask:0xf bank_mask:0xf bound_ctrl:1
	v_add_f32_dpp v159, v159, v159 row_shr:8 row_mask:0xf bank_mask:0xf bound_ctrl:1
	s_and_b32 s43, s43, 4
	v_add_f32_dpp v165, v165, v165 row_shr:8 row_mask:0xf bank_mask:0xf bound_ctrl:1
	v_mov_b32_dpp v166, v159 row_bcast:15 row_mask:0xa bank_mask:0xf
	v_add_f32_e32 v159, v159, v166
	v_mov_b32_e32 v166, v131
	s_xor_b32 s46, s43, 4
	s_mulk_i32 s46, 0x600
	v_mov_b32_dpp v166, v165 row_bcast:15 row_mask:0xa bank_mask:0xf
	v_add_f32_e32 v165, v165, v166
	v_mov_b32_e32 v166, v131
	v_sub_f32_e32 v156, v156, v133
	v_fma_f32 v156, v184, v156, v133
	v_mov_b32_dpp v166, v159 row_bcast:31 row_mask:0xc bank_mask:0xf
	v_add_f32_e32 v159, v159, v166
	v_mov_b32_e32 v166, v131
	v_readlane_b32 s45, v159, 63
	s_nop 0
	v_mov_b32_dpp v166, v165 row_bcast:31 row_mask:0xc bank_mask:0xf
	v_max_f32_e64 v159, s45, s45
	v_max_f32_e32 v159, 0x179abe15, v159
	v_rsq_f32_e32 v159, v159
	v_add_f32_e32 v165, v165, v166
	v_mul_f32_e32 v158, v158, v159
	v_add_u32_e32 v159, s46, v180
	ds_write2st64_b32 v159, v189, v158 offset1:1
	v_mul_f32_e32 v158, v146, v158
	v_readlane_b32 s45, v165, 63
	ds_write2st64_b32 v159, v158, v157 offset0:2 offset1:3
	ds_write2st64_b32 v159, v156, v130 offset0:4 offset1:5
	v_bfe_u32 v130, v156, 16, 1
	v_mov_b32_e32 v165, v131
	v_add3_u32 v130, v156, v130, s41
	v_lshl_add_u64 v[156:157], v[164:165], 1, s[18:19]
	global_store_short_d16_hi v[156:157], v130, off
	s_and_saveexec_b64 s[66:67], s[4:5]
	s_cbranch_execz .LBB0_1070
	v_lshl_add_u32 v130, s44, 6, v140
	v_lshl_add_u64 v[156:157], v[130:131], 2, s[36:37]
	v_mov_b32_e32 v130, s45
	global_store_dword v[156:157], v130, off
